# j4 + diff attention loop: softmax split by key half, PV MFMAs of the first 16 keys issue before the exp/convert of the other 16 keys
# baseline (speedup 1.0000x reference)
; __device__ __forceinline__ unsigned cvtpk(float lo, float hi) { return __builtin_bit_cast(unsigned, __builtin_convertvector(f32x2_cv{lo, hi}, bf16x2_cv)); }
; __device__ __forceinline__ float dot2bf(unsigned w, unsigned x, float acc) { return __builtin_amdgcn_fdot2_f32_bf16(__builtin_bit_cast(bf16x2_t, w), __builtin_bit_cast(bf16x2_t, x), acc, false); }
; template <int DK, int MODE, bool OUTF32> ...
;     ...
;             for (int r = 0; r < 16; ++r) p[r] = __builtin_amdgcn_exp2f((MODE == 2) ? fmaf(p[r], sc2, -m) : (p[r] - m));
;             bf16x8 pb0, pb1;
;             { const unsigned w0 = cvtpk(p[0], p[1]), w1 = cvtpk(p[2], p[3]), w2 = cvtpk(p[4], p[5]), w3 = cvtpk(p[6], p[7]);
;               const uint4 u = make_uint4(w0, w1, w2, w3); pb0 = *reinterpret_cast<const bf16x8*>(&u); }
;             { const unsigned w0 = cvtpk(p[8], p[9]), w1 = cvtpk(p[10], p[11]), w2 = cvtpk(p[12], p[13]), w3 = cvtpk(p[14], p[15]);
;               const uint4 u = make_uint4(w0, w1, w2, w3); pb1 = *reinterpret_cast<const bf16x8*>(&u); }
;             {
;                 const uint4 ua = *reinterpret_cast<const uint4*>(&pb0), ub = *reinterpret_cast<const uint4*>(&pb1);
;                 float ps = 0.f, ps2 = 0.f;
;                 ps = dot2bf(ua.x, 0x3f803f80u, ps); ps2 = dot2bf(ua.y, 0x3f803f80u, ps2); ps = dot2bf(ua.z, 0x3f803f80u, ps); ps2 = dot2bf(ua.w, 0x3f803f80u, ps2);
;                 ps = dot2bf(ub.x, 0x3f803f80u, ps); ps2 = dot2bf(ub.y, 0x3f803f80u, ps2); ps = dot2bf(ub.z, 0x3f803f80u, ps); ps2 = dot2bf(ub.w, 0x3f803f80u, ps2);
;                 l += ps + ps2;
;             }
;             if (HOISTK && !HOISTV) A_VREADS(0, 4);
;             if (HOISTK) __builtin_amdgcn_sched_barrier(0);
; #pragma unroll
;             for (int db = 0; db < 4; ++db) {
;                 if (!HOISTK) { A_VREADS(db, db + 1); }
;                 o[db] = __builtin_amdgcn_mfma_f32_32x32x16_bf16(vf[2 * db], pb0, o[db], 0, 0, 0);
;                 o[db] = __builtin_amdgcn_mfma_f32_32x32x16_bf16(vf[2 * db + 1], pb1, o[db], 0, 0, 0);
;             }
.LBB0_941:
	v_fma_f32 v68, v68, s24, -v181
	v_fma_f32 v69, v69, s24, -v181
	v_fma_f32 v70, v70, s24, -v181
	v_fma_f32 v71, v71, s24, -v181
	v_fma_f32 v72, v72, s24, -v181
	v_fma_f32 v73, v73, s24, -v181
	v_fma_f32 v74, v74, s24, -v181
	v_fma_f32 v75, v75, s24, -v181
	v_exp_f32_e32 v68, v68
	v_exp_f32_e32 v69, v69
	v_exp_f32_e32 v70, v70
	v_exp_f32_e32 v71, v71
	v_exp_f32_e32 v72, v72
	v_exp_f32_e32 v73, v73
	v_exp_f32_e32 v74, v74
	v_exp_f32_e32 v75, v75
	v_cvt_pk_bf16_f32 v68, v68, v69
	v_cvt_pk_bf16_f32 v69, v70, v71
	v_cvt_pk_bf16_f32 v70, v72, v73
	v_cvt_pk_bf16_f32 v71, v74, v75
	v_mov_b32_e32 v192, 0
	v_mov_b32_e32 v193, 0
	v_dot2c_f32_bf16_e32 v192, 0x3f803f80, v68
	v_dot2c_f32_bf16_e32 v193, 0x3f803f80, v69
	v_dot2c_f32_bf16_e32 v192, 0x3f803f80, v70
	v_dot2c_f32_bf16_e32 v193, 0x3f803f80, v71
	s_waitcnt lgkmcnt(7)
	v_mfma_f32_32x32x16_bf16 v[52:67], v[132:135], v[68:71], v[52:67]
	s_waitcnt lgkmcnt(5)
	v_mfma_f32_32x32x16_bf16 v[20:35], v[140:143], v[68:71], v[20:35]
	s_waitcnt lgkmcnt(3)
	v_mfma_f32_32x32x16_bf16 v[36:51], v[148:151], v[68:71], v[36:51]
	s_waitcnt lgkmcnt(1)
	v_mfma_f32_32x32x16_bf16 v[4:19], v[160:163], v[68:71], v[4:19]
	v_fma_f32 v76, v76, s24, -v181
	v_fma_f32 v77, v77, s24, -v181
	v_fma_f32 v78, v78, s24, -v181
	v_fma_f32 v79, v79, s24, -v181
	v_fma_f32 v80, v80, s24, -v181
	v_fma_f32 v81, v81, s24, -v181
	v_fma_f32 v82, v82, s24, -v181
	v_fma_f32 v83, v83, s24, -v181
	v_exp_f32_e32 v76, v76
	v_exp_f32_e32 v77, v77
	v_exp_f32_e32 v78, v78
	v_exp_f32_e32 v79, v79
	v_exp_f32_e32 v80, v80
	v_exp_f32_e32 v81, v81
	v_exp_f32_e32 v82, v82
	v_exp_f32_e32 v83, v83
	v_cvt_pk_bf16_f32 v72, v76, v77
	v_cvt_pk_bf16_f32 v73, v78, v79
	v_cvt_pk_bf16_f32 v74, v80, v81
	v_cvt_pk_bf16_f32 v75, v82, v83
	v_dot2c_f32_bf16_e32 v192, 0x3f803f80, v72
	v_dot2c_f32_bf16_e32 v193, 0x3f803f80, v73
	v_dot2c_f32_bf16_e32 v192, 0x3f803f80, v74
	v_dot2c_f32_bf16_e32 v193, 0x3f803f80, v75
	s_nop 2
	v_add_f32_e32 v192, v192, v193
	v_mfma_f32_32x32x16_bf16 v[52:67], v[136:139], v[72:75], v[52:67]
	v_add_f32_e32 v179, v179, v192
	v_mfma_f32_32x32x16_bf16 v[20:35], v[144:147], v[72:75], v[20:35]
	v_mfma_f32_32x32x16_bf16 v[36:51], v[152:155], v[72:75], v[36:51]
	s_waitcnt lgkmcnt(0)
	v_mfma_f32_32x32x16_bf16 v[4:19], v[156:159], v[72:75], v[4:19]
